# plus one static s_setprio 1 for waves 4-7 during the attention phase (reset to 0 after it)
# baseline (speedup 1.0000x reference)
; __device__ __forceinline__ int opaque_tid() { int t = threadIdx.x; asm volatile("" : "+v"(t)); return t; }
; __global__ void __launch_bounds__(NTHR) mega_fwd(Params p) {
;     ...
;         for (int rep3 = 0; rep3 < REP_S3; ++rep3) {
;             const int tid = opaque_tid(), lane = tid & 63, wave = __builtin_amdgcn_readfirstlane(tid >> 6), gw = bx * NWAVES + wave; (void)tid; (void)lane; (void)gw;
;             const float lam_init = l == 0 ? 0.2f : 0.35550906759096934f;
;             float lam; { const float* lp = p.diff_lambda + l * 256; const float sa = wave_sum(lp[lane] * lp[64 + lane]), sb = wave_sum(lp[128 + lane] * lp[192 + lane]); lam = expf(sa) - expf(sb) + lam_init; }
;             constexpr float C64 = 0.125f * 1.4426950408889634f, THR64 = att::THR / 0.125f;
;             constexpr float SC128 = 0.08838834764831845f, C128 = SC128 * 1.4426950408889634f, THR128 = att::THR / SC128;
;             const int r32 = lane & 31, hi = lane >> 5;
;             unsigned* ccnt = CTL + 32768 + l * 2048;
;             if (ON_CONV && bx >= 128) {
.LBB0_366:
	s_lshr_b32 s0, s33, 8
	s_cmp_eq_u32 s0, 0
	s_cbranch_scc1 .Ls3prio_skip
	s_setprio 1

; __global__ void __launch_bounds__(NTHR) mega_fwd(Params p) {
;     ...
;             __syncthreads();
;             if (G - 1 - bx < 64) {
;                 if (tid == 0) { unsigned sp = 0; while (__hip_atomic_load(ccnt + 64 * ((G - 1 - bx) >> 1), __ATOMIC_RELAXED, __HIP_MEMORY_SCOPE_AGENT) < 8u) { __builtin_amdgcn_s_sleep(2); if (++sp > (1u << 24)) break; }
;                     __builtin_amdgcn_fence(__ATOMIC_ACQUIRE, "agent"); asm volatile("s_waitcnt vmcnt(0)" ::: "memory"); }
.LBB0_719:
	s_setprio 0
	v_readlane_b32 s2, v253, 20
	v_readlane_b32 s3, v253, 21
	s_andn2_b64 vcc, exec, s[2:3]
	s_barrier
	v_cndmask_b32_e64 v0, 0, 1, s[2:3]
	v_cmp_ne_u32_e64 s[0:1], 1, v0
	s_cbranch_vccnz .LBB0_736
	v_cmp_eq_u32_e32 vcc, 0, v154
	s_and_saveexec_b64 s[2:3], vcc
	s_cbranch_execz .LBB0_735
	v_readlane_b32 s4, v254, 36
	v_readlane_b32 s6, v255, 20
	v_readlane_b32 s5, v254, 37
	s_add_u32 s4, s6, s4
	v_readlane_b32 s6, v255, 23
	s_addc_u32 s5, s6, s5
	s_mov_b32 s8, 0x1000000
	s_branch .LBB0_724
